# Up epilogue: waves 4-7 (the SIMD partners of waves 0-3) start the epilogue 6x64 cycles later (s_sleep 6 after the halo barrier) so partner waves do not hit their store instructions at the same time
# baseline (speedup 1.0000x reference)
; #define LAS __attribute__((address_space(3)))
;     __device__ __forceinline__ void operator()(const f32x4 (&acc)[2][2][4][2], const pg8::Unit& u, int ui, int wr, int wc, int fr, int fq) const {
;     ...
;         asm volatile("s_waitcnt lgkmcnt(0)" ::: "memory"); __builtin_amdgcn_s_barrier(); asm volatile("" ::: "memory");
; #pragma unroll
;         for (int ai = 0; ai < 2; ++ai) {
;             f32x4 pv[2];
;             if (ai == 0 && wr == 0) { pv[0] = (f32x4){0.f, 0.f, 0.f, 0.f}; pv[1] = pv[0]; }
;             else { const int pai = (wr == 1) ? ai : ai - 1, pwr = wr ^ 1; const int xr = (fr >= 14) ? fr - 14 : 0;
; #pragma unroll
;                 for (int n = 0; n < 2; ++n) pv[n] = *(const LAS f32x4*)(xch + ((pai * 2 + pwr) * 4 + wc) * 64 + xr * 32 + 8 * fq + 4 * n); }
.LBB0_237:
	s_or_b64 exec, exec, s[18:19]
	s_waitcnt lgkmcnt(0)
	s_barrier
	s_and_b64 vcc, exec, s[74:75]
	s_cbranch_vccz .Lup_nostagger
	s_sleep 6
.Lup_nostagger:
	v_mov_b32_e32 v162, 0
	s_andn2_b64 vcc, exec, s[74:75]
	s_mov_b64 s[18:19], s[76:77]
	v_mov_b32_e32 v163, 0
	v_mov_b32_e32 v164, 0
	v_mov_b32_e32 v165, 0
	v_mov_b32_e32 v166, 0
	v_mov_b32_e32 v167, 0
	v_mov_b32_e32 v168, 0
	v_mov_b32_e32 v169, 0
	s_cbranch_vccnz .LBB0_239
	ds_read_b128 v[162:165], v219
	ds_read_b128 v[166:169], v219 offset:16
	s_andn2_b64 s[18:19], s[76:77], exec
